# epiall: hand-written in-proj epilogue for all tile classes (rotary, plain, z); compiler EpiIn unreachable
# baseline (speedup 1.0000x reference)
; #define GAS __attribute__((address_space(1)))
; __device__ __forceinline__ unsigned cvt_pk_bf16(float lo, float hi) { unsigned r; asm volatile("v_cvt_pk_bf16_f32 %0, %1, %2" : "=v"(r) : "v"(lo), "v"(hi)); return r; }
;     __device__ __forceinline__ void operator()(const f32x4 (&acc)[2][2][4][2], const Unit& u, int wr, int wc, int fr, int fq, const PG8_LAS float* tab) const {
;     ...
;                 const int row = u.pm * BM + ai * HALF + wr * 64 + m * 16 + fr;
;                 const float rs = rsqrtf(tab[ai * HALF + wr * 64 + m * 16 + fr] * (1.0f / 2048.0f) + 1e-6f);
;                 const int pos = row < 16384 ? (row & 8191) : (row - 16384);
;                 GAS bf16_t* rowp = (GAS bf16_t*)P + (size_t)row * 5120;
;                 if (is_z) {
;                     const f32x4 z0 = (acc[ai][0][m][0] * rs) * (acc[ai][1][m][0] * rs), z1 = (acc[ai][0][m][1] * rs) * (acc[ai][1][m][1] * rs);
;                     u32x4 w; w.x = cvt_pk_bf16(z0[0], z0[1]); w.y = cvt_pk_bf16(z0[2], z0[3]); w.z = cvt_pk_bf16(z1[0], z1[1]); w.w = cvt_pk_bf16(z1[2], z1[3]);
;                     *(GAS u32x4*)(rowp + 4608 + (pn - 18) * 128 + wc * 32 + 8 * fq) = w;
.Lei_z:
	s_and_b32 s4, s3, 1
	s_lshl_b32 s4, s4, 10
	v_add_u32_e32 v171, s4, v172
	ds_read_b32 v154, v171 offset:0
	ds_read_b32 v156, v171 offset:64
	ds_read_b32 v158, v171 offset:128
	ds_read_b32 v160, v171 offset:192
	ds_read_b32 v155, v171 offset:512
	ds_read_b32 v157, v171 offset:576
	ds_read_b32 v159, v171 offset:640
	ds_read_b32 v161, v171 offset:704
	s_mul_i32 s4, s1, 0x280000
	s_lshl_b32 s5, s0, 8
	s_add_u32 s4, s4, s5
	s_add_u32 s4, s4, 0x1200
	s_add_u32 s6, s86, s4
	s_addc_u32 s7, s87, 0
	v_mul_u32_u24_e32 v170, 0x2800, v1
	v_lshl_add_u32 v170, v173, 1, v170
	s_waitcnt lgkmcnt(0)
	v_fmamk_f32 v154, v154, 0x3a000000, v236
	v_fmamk_f32 v156, v156, 0x3a000000, v236
	v_fmamk_f32 v158, v158, 0x3a000000, v236
	v_fmamk_f32 v160, v160, 0x3a000000, v236
	v_fmamk_f32 v155, v155, 0x3a000000, v236
	v_fmamk_f32 v157, v157, 0x3a000000, v236
	v_fmamk_f32 v159, v159, 0x3a000000, v236
	v_fmamk_f32 v161, v161, 0x3a000000, v236
	v_rsq_f32_e32 v154, v154
	v_rsq_f32_e32 v156, v156
	v_rsq_f32_e32 v158, v158
	v_rsq_f32_e32 v160, v160
	v_rsq_f32_e32 v155, v155
	v_rsq_f32_e32 v157, v157
	v_rsq_f32_e32 v159, v159
	v_rsq_f32_e32 v161, v161
	v_pk_mul_f32 v[126:127], v[126:127], v[154:155] op_sel_hi:[1,0]
	v_pk_mul_f32 v[128:129], v[128:129], v[154:155] op_sel_hi:[1,0]
	v_pk_mul_f32 v[122:123], v[122:123], v[154:155] op_sel_hi:[1,0]
	v_pk_mul_f32 v[124:125], v[124:125], v[154:155] op_sel_hi:[1,0]
	v_pk_mul_f32 v[118:119], v[118:119], v[154:155] op_sel_hi:[1,0]
	v_pk_mul_f32 v[120:121], v[120:121], v[154:155] op_sel_hi:[1,0]
	v_pk_mul_f32 v[114:115], v[114:115], v[154:155] op_sel_hi:[1,0]
	v_pk_mul_f32 v[116:117], v[116:117], v[154:155] op_sel_hi:[1,0]
	v_pk_mul_f32 v[126:127], v[126:127], v[118:119]
	v_pk_mul_f32 v[128:129], v[128:129], v[120:121]
	v_pk_mul_f32 v[122:123], v[122:123], v[114:115]
	v_pk_mul_f32 v[124:125], v[124:125], v[116:117]
	v_cvt_pk_bf16_f32 v162, v126, v127
	v_cvt_pk_bf16_f32 v163, v128, v129
	v_cvt_pk_bf16_f32 v164, v122, v123
	v_cvt_pk_bf16_f32 v165, v124, v125
	s_mov_b64 s[10:11], s[6:7]
	global_store_dwordx4 v170, v[162:165], s[10:11]
	v_pk_mul_f32 v[110:111], v[110:111], v[156:157] op_sel_hi:[1,0]
	v_pk_mul_f32 v[112:113], v[112:113], v[156:157] op_sel_hi:[1,0]
	v_pk_mul_f32 v[106:107], v[106:107], v[156:157] op_sel_hi:[1,0]
	v_pk_mul_f32 v[108:109], v[108:109], v[156:157] op_sel_hi:[1,0]
	v_pk_mul_f32 v[102:103], v[102:103], v[156:157] op_sel_hi:[1,0]
	v_pk_mul_f32 v[104:105], v[104:105], v[156:157] op_sel_hi:[1,0]
	v_pk_mul_f32 v[98:99], v[98:99], v[156:157] op_sel_hi:[1,0]
	v_pk_mul_f32 v[100:101], v[100:101], v[156:157] op_sel_hi:[1,0]
	v_pk_mul_f32 v[110:111], v[110:111], v[102:103]
	v_pk_mul_f32 v[112:113], v[112:113], v[104:105]
	v_pk_mul_f32 v[106:107], v[106:107], v[98:99]
	v_pk_mul_f32 v[108:109], v[108:109], v[100:101]
	v_cvt_pk_bf16_f32 v166, v110, v111
	v_cvt_pk_bf16_f32 v167, v112, v113
	v_cvt_pk_bf16_f32 v168, v106, v107
	v_cvt_pk_bf16_f32 v169, v108, v109
	s_add_u32 s10, s6, 0x28000
	s_addc_u32 s11, s7, 0
	global_store_dwordx4 v170, v[166:169], s[10:11]
	v_pk_mul_f32 v[94:95], v[94:95], v[158:159] op_sel_hi:[1,0]
	v_pk_mul_f32 v[96:97], v[96:97], v[158:159] op_sel_hi:[1,0]
	v_pk_mul_f32 v[90:91], v[90:91], v[158:159] op_sel_hi:[1,0]
	v_pk_mul_f32 v[92:93], v[92:93], v[158:159] op_sel_hi:[1,0]
	v_pk_mul_f32 v[86:87], v[86:87], v[158:159] op_sel_hi:[1,0]
	v_pk_mul_f32 v[88:89], v[88:89], v[158:159] op_sel_hi:[1,0]
	v_pk_mul_f32 v[82:83], v[82:83], v[158:159] op_sel_hi:[1,0]
	v_pk_mul_f32 v[84:85], v[84:85], v[158:159] op_sel_hi:[1,0]
	v_pk_mul_f32 v[94:95], v[94:95], v[86:87]
	v_pk_mul_f32 v[96:97], v[96:97], v[88:89]
	v_pk_mul_f32 v[90:91], v[90:91], v[82:83]
	v_pk_mul_f32 v[92:93], v[92:93], v[84:85]
	v_cvt_pk_bf16_f32 v162, v94, v95
	v_cvt_pk_bf16_f32 v163, v96, v97
	v_cvt_pk_bf16_f32 v164, v90, v91
	v_cvt_pk_bf16_f32 v165, v92, v93
	s_add_u32 s10, s6, 0x50000
	s_addc_u32 s11, s7, 0
	global_store_dwordx4 v170, v[162:165], s[10:11]
	v_pk_mul_f32 v[78:79], v[78:79], v[160:161] op_sel_hi:[1,0]
	v_pk_mul_f32 v[80:81], v[80:81], v[160:161] op_sel_hi:[1,0]
	v_pk_mul_f32 v[74:75], v[74:75], v[160:161] op_sel_hi:[1,0]
	v_pk_mul_f32 v[76:77], v[76:77], v[160:161] op_sel_hi:[1,0]
	v_pk_mul_f32 v[70:71], v[70:71], v[160:161] op_sel_hi:[1,0]
; #define GAS __attribute__((address_space(1)))
; __device__ __forceinline__ unsigned cvt_pk_bf16(float lo, float hi) { unsigned r; asm volatile("v_cvt_pk_bf16_f32 %0, %1, %2" : "=v"(r) : "v"(lo), "v"(hi)); return r; }
;     __device__ __forceinline__ void operator()(const f32x4 (&acc)[2][2][4][2], const Unit& u, int wr, int wc, int fr, int fq, const PG8_LAS float* tab) const {
;     ...
;                 const int row = u.pm * BM + ai * HALF + wr * 64 + m * 16 + fr;
;                 const float rs = rsqrtf(tab[ai * HALF + wr * 64 + m * 16 + fr] * (1.0f / 2048.0f) + 1e-6f);
;                 const int pos = row < 16384 ? (row & 8191) : (row - 16384);
;                 GAS bf16_t* rowp = (GAS bf16_t*)P + (size_t)row * 5120;
;                 if (is_z) {
;                     const f32x4 z0 = (acc[ai][0][m][0] * rs) * (acc[ai][1][m][0] * rs), z1 = (acc[ai][0][m][1] * rs) * (acc[ai][1][m][1] * rs);
;                     u32x4 w; w.x = cvt_pk_bf16(z0[0], z0[1]); w.y = cvt_pk_bf16(z0[2], z0[3]); w.z = cvt_pk_bf16(z1[0], z1[1]); w.w = cvt_pk_bf16(z1[2], z1[3]);
;                     *(GAS u32x4*)(rowp + 4608 + (pn - 18) * 128 + wc * 32 + 8 * fq) = w;
	v_pk_mul_f32 v[72:73], v[72:73], v[160:161] op_sel_hi:[1,0]
	v_pk_mul_f32 v[66:67], v[66:67], v[160:161] op_sel_hi:[1,0]
	v_pk_mul_f32 v[68:69], v[68:69], v[160:161] op_sel_hi:[1,0]
	v_pk_mul_f32 v[78:79], v[78:79], v[70:71]
	v_pk_mul_f32 v[80:81], v[80:81], v[72:73]
	v_pk_mul_f32 v[74:75], v[74:75], v[66:67]
	v_pk_mul_f32 v[76:77], v[76:77], v[68:69]
	v_cvt_pk_bf16_f32 v166, v78, v79
	v_cvt_pk_bf16_f32 v167, v80, v81
	v_cvt_pk_bf16_f32 v168, v74, v75
	v_cvt_pk_bf16_f32 v169, v76, v77
	s_add_u32 s10, s6, 0x78000
	s_addc_u32 s11, s7, 0
	global_store_dwordx4 v170, v[166:169], s[10:11]
	v_mov_b32_e32 v154, v155
	v_mov_b32_e32 v156, v157
	v_mov_b32_e32 v158, v159
	v_mov_b32_e32 v160, v161
	v_pk_mul_f32 v[62:63], v[62:63], v[154:155] op_sel_hi:[1,0]
	v_pk_mul_f32 v[64:65], v[64:65], v[154:155] op_sel_hi:[1,0]
	v_pk_mul_f32 v[58:59], v[58:59], v[154:155] op_sel_hi:[1,0]
	v_pk_mul_f32 v[60:61], v[60:61], v[154:155] op_sel_hi:[1,0]
	v_pk_mul_f32 v[54:55], v[54:55], v[154:155] op_sel_hi:[1,0]
	v_pk_mul_f32 v[56:57], v[56:57], v[154:155] op_sel_hi:[1,0]
	v_pk_mul_f32 v[50:51], v[50:51], v[154:155] op_sel_hi:[1,0]
	v_pk_mul_f32 v[52:53], v[52:53], v[154:155] op_sel_hi:[1,0]
	v_pk_mul_f32 v[62:63], v[62:63], v[54:55]
	v_pk_mul_f32 v[64:65], v[64:65], v[56:57]
	v_pk_mul_f32 v[58:59], v[58:59], v[50:51]
	v_pk_mul_f32 v[60:61], v[60:61], v[52:53]
	v_cvt_pk_bf16_f32 v162, v62, v63
	v_cvt_pk_bf16_f32 v163, v64, v65
	v_cvt_pk_bf16_f32 v164, v58, v59
	v_cvt_pk_bf16_f32 v165, v60, v61
	s_add_u32 s10, s6, 0x140000
	s_addc_u32 s11, s7, 0
	global_store_dwordx4 v170, v[162:165], s[10:11]
	v_pk_mul_f32 v[46:47], v[46:47], v[156:157] op_sel_hi:[1,0]
	v_pk_mul_f32 v[48:49], v[48:49], v[156:157] op_sel_hi:[1,0]
	v_pk_mul_f32 v[42:43], v[42:43], v[156:157] op_sel_hi:[1,0]
	v_pk_mul_f32 v[44:45], v[44:45], v[156:157] op_sel_hi:[1,0]
	v_pk_mul_f32 v[38:39], v[38:39], v[156:157] op_sel_hi:[1,0]
	v_pk_mul_f32 v[40:41], v[40:41], v[156:157] op_sel_hi:[1,0]
	v_pk_mul_f32 v[34:35], v[34:35], v[156:157] op_sel_hi:[1,0]
	v_pk_mul_f32 v[36:37], v[36:37], v[156:157] op_sel_hi:[1,0]
	v_pk_mul_f32 v[46:47], v[46:47], v[38:39]
	v_pk_mul_f32 v[48:49], v[48:49], v[40:41]
	v_pk_mul_f32 v[42:43], v[42:43], v[34:35]
	v_pk_mul_f32 v[44:45], v[44:45], v[36:37]
	v_cvt_pk_bf16_f32 v166, v46, v47
	v_cvt_pk_bf16_f32 v167, v48, v49
	v_cvt_pk_bf16_f32 v168, v42, v43
	v_cvt_pk_bf16_f32 v169, v44, v45
	s_add_u32 s10, s6, 0x168000
	s_addc_u32 s11, s7, 0
	global_store_dwordx4 v170, v[166:169], s[10:11]
	v_pk_mul_f32 v[30:31], v[30:31], v[158:159] op_sel_hi:[1,0]
	v_pk_mul_f32 v[32:33], v[32:33], v[158:159] op_sel_hi:[1,0]
	v_pk_mul_f32 v[26:27], v[26:27], v[158:159] op_sel_hi:[1,0]
	v_pk_mul_f32 v[28:29], v[28:29], v[158:159] op_sel_hi:[1,0]
	v_pk_mul_f32 v[22:23], v[22:23], v[158:159] op_sel_hi:[1,0]
	v_pk_mul_f32 v[24:25], v[24:25], v[158:159] op_sel_hi:[1,0]
	v_pk_mul_f32 v[18:19], v[18:19], v[158:159] op_sel_hi:[1,0]
	v_pk_mul_f32 v[20:21], v[20:21], v[158:159] op_sel_hi:[1,0]
	v_pk_mul_f32 v[30:31], v[30:31], v[22:23]
	v_pk_mul_f32 v[32:33], v[32:33], v[24:25]
	v_pk_mul_f32 v[26:27], v[26:27], v[18:19]
	v_pk_mul_f32 v[28:29], v[28:29], v[20:21]
	v_cvt_pk_bf16_f32 v162, v30, v31
	v_cvt_pk_bf16_f32 v163, v32, v33
	v_cvt_pk_bf16_f32 v164, v26, v27
	v_cvt_pk_bf16_f32 v165, v28, v29
	s_add_u32 s10, s6, 0x190000
	s_addc_u32 s11, s7, 0
	global_store_dwordx4 v170, v[162:165], s[10:11]
	v_pk_mul_f32 v[14:15], v[14:15], v[160:161] op_sel_hi:[1,0]
	v_pk_mul_f32 v[16:17], v[16:17], v[160:161] op_sel_hi:[1,0]
	v_pk_mul_f32 v[10:11], v[10:11], v[160:161] op_sel_hi:[1,0]
	v_pk_mul_f32 v[12:13], v[12:13], v[160:161] op_sel_hi:[1,0]
	v_pk_mul_f32 v[6:7], v[6:7], v[160:161] op_sel_hi:[1,0]
	v_pk_mul_f32 v[8:9], v[8:9], v[160:161] op_sel_hi:[1,0]
	v_pk_mul_f32 v[2:3], v[2:3], v[160:161] op_sel_hi:[1,0]
	v_pk_mul_f32 v[4:5], v[4:5], v[160:161] op_sel_hi:[1,0]
	v_pk_mul_f32 v[14:15], v[14:15], v[6:7]
	v_pk_mul_f32 v[16:17], v[16:17], v[8:9]
	v_pk_mul_f32 v[10:11], v[10:11], v[2:3]
	v_pk_mul_f32 v[12:13], v[12:13], v[4:5]
	v_cvt_pk_bf16_f32 v166, v14, v15
	v_cvt_pk_bf16_f32 v167, v16, v17
	v_cvt_pk_bf16_f32 v168, v10, v11
	v_cvt_pk_bf16_f32 v169, v12, v13
	s_add_u32 s10, s6, 0x1b8000
	s_addc_u32 s11, s7, 0
	global_store_dwordx4 v170, v[166:169], s[10:11]
	s_branch .LBB0_406
